# GEMM units: accumulator zeroing with 64 v_mov_b64 instead of 128 v_mov_b32
# speedup vs baseline: 1.0059x; 1.0059x over previous
; template <class Epi, class Sched, bool ALIGN_EPI = false, bool SP2 = false>
; __device__ __forceinline__ void gemm_phase(PG8_LAS unsigned char* lds, const Gemm g, const Sched& S, const Epi& E, int wv) {
;     ...
;     for (;;) {
;         const bool has_next = S.next(ui + 1, nxt);
;         const char* nA = has_next ? (const char*)g.A + (size_t)nxt.pm * tstep : cA; const char* nB = has_next ? (const char*)g.Bt + (size_t)nxt.pn * tstep : cB;
;         for (int t = 0; t < nt; t += 2) {
;             const bool last = (t == nt - 2);
;             const char* a1 = cA + (size_t)(t + 1) * kstep;
;             const char* a2 = last ? nA : cA + (size_t)(t + 2) * kstep; const char* b2 = last ? nB : cB + (size_t)(t + 2) * kstep;
;     ...
; #pragma unroll
;         for (int a = 0; a < 2; ++a)
; #pragma unroll
;             for (int b = 0; b < 2; ++b)
; #pragma unroll
;                 for (int m = 0; m < 4; ++m)
; #pragma unroll
;                     for (int n = 0; n < 2; ++n) acc[a][b][m][n] = (f32x4){0.f, 0.f, 0.f, 0.f};
;         cur = nxt; cA = nA; cB = nB; ++ui;
.LBB0_90:
	s_ashr_i32 s15, s14, 31
	s_lshl_b64 s[16:17], s[14:15], 20
	s_add_u32 s16, s6, s16
	s_addc_u32 s17, s7, s17
	s_and_b64 s[18:19], s[10:11], exec
	s_cselect_b32 s15, s17, s23
	s_cselect_b32 s47, s16, s22
	s_ashr_i32 s13, s12, 31
	s_lshl_b64 s[18:19], s[12:13], 20
	s_add_u32 s18, s33, s18
	s_addc_u32 s19, s34, s19
	s_and_b64 s[28:29], s[10:11], exec
	s_cselect_b32 s13, s19, s25
	s_cselect_b32 s48, s18, s24
	s_add_u32 s22, s22, 0x80080
	s_addc_u32 s23, s23, 0
	s_add_u32 s49, s24, 0x100
	s_nop 0
	s_addc_u32 s50, s25, 0
	s_mov_b32 s51, -2
	v_mov_b64_e32 v[0:1], 0
	v_mov_b64_e32 v[2:3], 0
	v_mov_b64_e32 v[4:5], 0
	v_mov_b64_e32 v[6:7], 0
	v_mov_b64_e32 v[8:9], 0
	v_mov_b64_e32 v[10:11], 0
	v_mov_b64_e32 v[12:13], 0
	v_mov_b64_e32 v[14:15], 0
	v_mov_b64_e32 v[16:17], 0
	v_mov_b64_e32 v[18:19], 0
	v_mov_b64_e32 v[20:21], 0
	v_mov_b64_e32 v[22:23], 0
	v_mov_b64_e32 v[24:25], 0
	v_mov_b64_e32 v[26:27], 0
	v_mov_b64_e32 v[28:29], 0
	v_mov_b64_e32 v[30:31], 0
	v_mov_b64_e32 v[32:33], 0
	v_mov_b64_e32 v[34:35], 0
	v_mov_b64_e32 v[36:37], 0
	v_mov_b64_e32 v[38:39], 0
	v_mov_b64_e32 v[40:41], 0
	v_mov_b64_e32 v[42:43], 0
	v_mov_b64_e32 v[44:45], 0
	v_mov_b64_e32 v[46:47], 0
	v_mov_b64_e32 v[48:49], 0
	v_mov_b64_e32 v[50:51], 0
	v_mov_b64_e32 v[52:53], 0
	v_mov_b64_e32 v[54:55], 0
	v_mov_b64_e32 v[56:57], 0
	v_mov_b64_e32 v[58:59], 0
	v_mov_b64_e32 v[60:61], 0
	v_mov_b64_e32 v[62:63], 0
	v_mov_b64_e32 v[64:65], 0
	v_mov_b64_e32 v[66:67], 0
	v_mov_b64_e32 v[68:69], 0
	v_mov_b64_e32 v[70:71], 0
	v_mov_b64_e32 v[72:73], 0
	v_mov_b64_e32 v[74:75], 0
	v_mov_b64_e32 v[76:77], 0
	v_mov_b64_e32 v[78:79], 0
	v_mov_b64_e32 v[80:81], 0
	v_mov_b64_e32 v[82:83], 0
	v_mov_b64_e32 v[84:85], 0
	v_mov_b64_e32 v[86:87], 0
	v_mov_b64_e32 v[88:89], 0
	v_mov_b64_e32 v[90:91], 0
	v_mov_b64_e32 v[92:93], 0
	v_mov_b64_e32 v[94:95], 0
	v_mov_b64_e32 v[96:97], 0
	v_mov_b64_e32 v[98:99], 0
	v_mov_b64_e32 v[100:101], 0
	v_mov_b64_e32 v[102:103], 0
	v_mov_b64_e32 v[104:105], 0
	v_mov_b64_e32 v[106:107], 0
	v_mov_b64_e32 v[108:109], 0
	v_mov_b64_e32 v[110:111], 0
	v_mov_b64_e32 v[112:113], 0
	v_mov_b64_e32 v[114:115], 0
	v_mov_b64_e32 v[116:117], 0
	v_mov_b64_e32 v[118:119], 0
	v_mov_b64_e32 v[120:121], 0
	v_mov_b64_e32 v[122:123], 0
	v_mov_b64_e32 v[124:125], 0
	v_mov_b64_e32 v[126:127], 0

; template <class Epi, class Sched, bool ALIGN_EPI = false, bool SP2 = false>
; __device__ __forceinline__ void gemm_phase(PG8_LAS unsigned char* lds, const Gemm g, const Sched& S, const Epi& E, int wv) {
;     ...
;     for (;;) {
;         const bool has_next = S.next(ui + 1, nxt);
;         const char* nA = has_next ? (const char*)g.A + (size_t)nxt.pm * tstep : cA; const char* nB = has_next ? (const char*)g.Bt + (size_t)nxt.pn * tstep : cB;
;         for (int t = 0; t < nt; t += 2) {
;             const bool last = (t == nt - 2);
;             const char* a1 = cA + (size_t)(t + 1) * kstep;
;             const char* a2 = last ? nA : cA + (size_t)(t + 2) * kstep; const char* b2 = last ? nB : cB + (size_t)(t + 2) * kstep;
;     ...
; #pragma unroll
;         for (int a = 0; a < 2; ++a)
; #pragma unroll
;             for (int b = 0; b < 2; ++b)
; #pragma unroll
;                 for (int m = 0; m < 4; ++m)
; #pragma unroll
;                     for (int n = 0; n < 2; ++n) acc[a][b][m][n] = (f32x4){0.f, 0.f, 0.f, 0.f};
;         cur = nxt; cA = nA; cB = nB; ++ui;
.LBB0_119:
	s_ashr_i32 s21, s20, 31
	s_lshl_b64 s[38:39], s[20:21], 20
	s_add_u32 s38, s64, s38
	s_addc_u32 s39, s65, s39
	s_and_b64 s[40:41], s[36:37], exec
	s_cselect_b32 s7, s39, s35
	s_cselect_b32 s21, s38, s34
	s_ashr_i32 s19, s18, 31
	s_lshl_b64 s[40:41], s[18:19], 20
	s_add_u32 s40, s1, s40
	s_addc_u32 s41, s2, s41
	s_and_b64 s[46:47], s[36:37], exec
	s_cselect_b32 s19, s41, s45
	s_cselect_b32 s48, s40, s44
	s_add_u32 s34, s34, 0x80080
	s_addc_u32 s35, s35, 0
	s_add_u32 s49, s44, 0x100
	s_nop 0
	s_addc_u32 s50, s45, 0
	s_mov_b32 s51, -2
	v_mov_b64_e32 v[0:1], 0
	v_mov_b64_e32 v[2:3], 0
	v_mov_b64_e32 v[4:5], 0
	v_mov_b64_e32 v[6:7], 0
	v_mov_b64_e32 v[8:9], 0
	v_mov_b64_e32 v[10:11], 0
	v_mov_b64_e32 v[12:13], 0
	v_mov_b64_e32 v[14:15], 0
	v_mov_b64_e32 v[16:17], 0
	v_mov_b64_e32 v[18:19], 0
	v_mov_b64_e32 v[20:21], 0
	v_mov_b64_e32 v[22:23], 0
	v_mov_b64_e32 v[24:25], 0
	v_mov_b64_e32 v[26:27], 0
	v_mov_b64_e32 v[28:29], 0
	v_mov_b64_e32 v[30:31], 0
	v_mov_b64_e32 v[32:33], 0
	v_mov_b64_e32 v[34:35], 0
	v_mov_b64_e32 v[36:37], 0
	v_mov_b64_e32 v[38:39], 0
	v_mov_b64_e32 v[40:41], 0
	v_mov_b64_e32 v[42:43], 0
	v_mov_b64_e32 v[44:45], 0
	v_mov_b64_e32 v[46:47], 0
	v_mov_b64_e32 v[48:49], 0
	v_mov_b64_e32 v[50:51], 0
	v_mov_b64_e32 v[52:53], 0
	v_mov_b64_e32 v[54:55], 0
	v_mov_b64_e32 v[56:57], 0
	v_mov_b64_e32 v[58:59], 0
	v_mov_b64_e32 v[60:61], 0
	v_mov_b64_e32 v[62:63], 0
	v_mov_b64_e32 v[64:65], 0
	v_mov_b64_e32 v[66:67], 0
	v_mov_b64_e32 v[68:69], 0
	v_mov_b64_e32 v[70:71], 0
	v_mov_b64_e32 v[72:73], 0
	v_mov_b64_e32 v[74:75], 0
	v_mov_b64_e32 v[76:77], 0
	v_mov_b64_e32 v[78:79], 0
	v_mov_b64_e32 v[80:81], 0
	v_mov_b64_e32 v[82:83], 0
	v_mov_b64_e32 v[84:85], 0
	v_mov_b64_e32 v[86:87], 0
	v_mov_b64_e32 v[88:89], 0
	v_mov_b64_e32 v[90:91], 0
	v_mov_b64_e32 v[92:93], 0
	v_mov_b64_e32 v[94:95], 0
	v_mov_b64_e32 v[96:97], 0
	v_mov_b64_e32 v[98:99], 0
	v_mov_b64_e32 v[100:101], 0
	v_mov_b64_e32 v[102:103], 0
	v_mov_b64_e32 v[104:105], 0
	v_mov_b64_e32 v[106:107], 0
	v_mov_b64_e32 v[108:109], 0
	v_mov_b64_e32 v[110:111], 0
	v_mov_b64_e32 v[112:113], 0
	v_mov_b64_e32 v[114:115], 0
	v_mov_b64_e32 v[116:117], 0
	v_mov_b64_e32 v[118:119], 0
	v_mov_b64_e32 v[120:121], 0
	v_mov_b64_e32 v[122:123], 0
	v_mov_b64_e32 v[124:125], 0
	v_mov_b64_e32 v[126:127], 0

; template <class Epi, class Sched, bool ALIGN_EPI = false, bool SP2 = false>
; __device__ __forceinline__ void gemm_phase(PG8_LAS unsigned char* lds, const Gemm g, const Sched& S, const Epi& E, int wv) {
;     ...
;     for (;;) {
;         const bool has_next = S.next(ui + 1, nxt);
;         const char* nA = has_next ? (const char*)g.A + (size_t)nxt.pm * tstep : cA; const char* nB = has_next ? (const char*)g.Bt + (size_t)nxt.pn * tstep : cB;
;         for (int t = 0; t < nt; t += 2) {
;             const bool last = (t == nt - 2);
;             const char* a1 = cA + (size_t)(t + 1) * kstep;
;             const char* a2 = last ? nA : cA + (size_t)(t + 2) * kstep; const char* b2 = last ? nB : cB + (size_t)(t + 2) * kstep;
;     ...
; #pragma unroll
;         for (int a = 0; a < 2; ++a)
; #pragma unroll
;             for (int b = 0; b < 2; ++b)
; #pragma unroll
;                 for (int m = 0; m < 4; ++m)
; #pragma unroll
;                     for (int n = 0; n < 2; ++n) acc[a][b][m][n] = (f32x4){0.f, 0.f, 0.f, 0.f};
;         cur = nxt; cA = nA; cB = nB; ++ui;
.LBB0_342:
	s_ashr_i32 s21, s20, 31
	s_lshl_b64 s[44:45], s[20:21], 20
	s_add_u32 s44, s82, s44
	s_addc_u32 s45, s83, s45
	s_and_b64 s[46:47], s[38:39], exec
	s_cselect_b32 s7, s45, s41
	s_cselect_b32 s21, s44, s40
	s_ashr_i32 s19, s18, 31
	s_lshl_b64 s[46:47], s[18:19], 20
	s_add_u32 s46, s0, s46
	s_addc_u32 s47, s1, s47
	s_and_b64 s[50:51], s[38:39], exec
	s_cselect_b32 s19, s47, s49
	s_cselect_b32 s35, s46, s48
	s_add_u32 s40, s40, 0x80080
	s_addc_u32 s41, s41, 0
	s_add_u32 s52, s48, 0x100
	s_nop 0
	s_addc_u32 s53, s49, 0
	s_mov_b32 s54, -2
	v_mov_b64_e32 v[0:1], 0
	v_mov_b64_e32 v[2:3], 0
	v_mov_b64_e32 v[4:5], 0
	v_mov_b64_e32 v[6:7], 0
	v_mov_b64_e32 v[8:9], 0
	v_mov_b64_e32 v[10:11], 0
	v_mov_b64_e32 v[12:13], 0
	v_mov_b64_e32 v[14:15], 0
	v_mov_b64_e32 v[16:17], 0
	v_mov_b64_e32 v[18:19], 0
	v_mov_b64_e32 v[20:21], 0
	v_mov_b64_e32 v[22:23], 0
	v_mov_b64_e32 v[24:25], 0
	v_mov_b64_e32 v[26:27], 0
	v_mov_b64_e32 v[28:29], 0
	v_mov_b64_e32 v[30:31], 0
	v_mov_b64_e32 v[32:33], 0
	v_mov_b64_e32 v[34:35], 0
	v_mov_b64_e32 v[36:37], 0
	v_mov_b64_e32 v[38:39], 0
	v_mov_b64_e32 v[40:41], 0
	v_mov_b64_e32 v[42:43], 0
	v_mov_b64_e32 v[44:45], 0
	v_mov_b64_e32 v[46:47], 0
	v_mov_b64_e32 v[48:49], 0
	v_mov_b64_e32 v[50:51], 0
	v_mov_b64_e32 v[52:53], 0
	v_mov_b64_e32 v[54:55], 0
	v_mov_b64_e32 v[56:57], 0
	v_mov_b64_e32 v[58:59], 0
	v_mov_b64_e32 v[60:61], 0
	v_mov_b64_e32 v[62:63], 0
	v_mov_b64_e32 v[64:65], 0
	v_mov_b64_e32 v[66:67], 0
	v_mov_b64_e32 v[68:69], 0
	v_mov_b64_e32 v[70:71], 0
	v_mov_b64_e32 v[72:73], 0
	v_mov_b64_e32 v[74:75], 0
	v_mov_b64_e32 v[76:77], 0
	v_mov_b64_e32 v[78:79], 0
	v_mov_b64_e32 v[80:81], 0
	v_mov_b64_e32 v[82:83], 0
	v_mov_b64_e32 v[84:85], 0
	v_mov_b64_e32 v[86:87], 0
	v_mov_b64_e32 v[88:89], 0
	v_mov_b64_e32 v[90:91], 0
	v_mov_b64_e32 v[92:93], 0
	v_mov_b64_e32 v[94:95], 0
	v_mov_b64_e32 v[96:97], 0
	v_mov_b64_e32 v[98:99], 0
	v_mov_b64_e32 v[100:101], 0
	v_mov_b64_e32 v[102:103], 0
	v_mov_b64_e32 v[104:105], 0
	v_mov_b64_e32 v[106:107], 0
	v_mov_b64_e32 v[108:109], 0
	v_mov_b64_e32 v[110:111], 0
	v_mov_b64_e32 v[112:113], 0
	v_mov_b64_e32 v[114:115], 0
	v_mov_b64_e32 v[116:117], 0
	v_mov_b64_e32 v[118:119], 0
	v_mov_b64_e32 v[120:121], 0
	v_mov_b64_e32 v[122:123], 0
	v_mov_b64_e32 v[124:125], 0
	v_mov_b64_e32 v[126:127], 0
